# v026 (MLA -m splat + K hoist) plus removal of the redundant pre-DMA workgroup barrier in unit prologues
# speedup vs baseline: 1.0081x; 1.0081x over previous
.LBB0_169:
	s_and_b32 s0, s64, 31
	s_lshl_b32 s0, s0, 6
	s_or_b32 s14, s14, s0
	s_mul_i32 s0, s15, 0x600
	s_mul_hi_u32 s1, s14, 0x600
	s_add_i32 s1, s1, s0
	s_mul_i32 s0, s14, 0x600
	s_add_u32 s0, s38, s0
	s_addc_u32 s1, s39, s1
	s_mul_hi_i32 s3, s2, 0xc0000
	s_mul_i32 s2, s2, 0xc0000
	v_mov_b32_e32 v158, v218
	s_add_u32 s4, s28, s2
	v_mov_b32_e32 v4, v218
	s_addc_u32 s5, s29, s3
	s_add_i32 s3, 0, 0x14000
	v_and_b32_e32 v0, 0x3fffffc0, v4
	v_lshl_add_u32 v159, v0, 2, s3
	v_ashrrev_i32_e32 v0, 6, v4
	v_and_b32_e32 v6, 31, v4
	v_readfirstlane_b32 s3, v0
	v_lshlrev_b32_e32 v0, 5, v0
	v_and_or_b32 v0, v0, 32, v6
	v_mul_u32_u24_e32 v0, 0x300, v0
	v_ashrrev_i32_e32 v2, 7, v4
	v_lshlrev_b32_e32 v184, 1, v0
	v_mul_lo_u32 v2, v2, s60
	v_lshl_add_u64 v[0:1], s[0:1], 0, v[184:185]
	v_ashrrev_i32_e32 v3, 31, v2
	v_lshl_add_u64 v[0:1], v[2:3], 1, v[0:1]
	v_lshrrev_b32_e32 v2, 1, v4
	v_and_b32_e32 v5, 63, v4
	v_and_b32_e32 v184, 16, v2
	v_lshl_add_u64 v[0:1], v[0:1], 0, v[184:185]
	s_lshl_b32 s6, s3, 10
	v_lshlrev_b32_e32 v3, 4, v5
	global_load_dwordx4 v[96:99], v[0:1], off
	global_load_dwordx4 v[100:103], v[0:1], off offset:32
	global_load_dwordx4 v[104:107], v[0:1], off offset:64
	global_load_dwordx4 v[108:111], v[0:1], off offset:96
	global_load_dwordx4 v[112:115], v[0:1], off offset:128
	global_load_dwordx4 v[116:119], v[0:1], off offset:160
	global_load_dwordx4 v[120:123], v[0:1], off offset:192
	global_load_dwordx4 v[124:127], v[0:1], off offset:224
	global_load_dwordx4 v[128:131], v[0:1], off offset:256
	global_load_dwordx4 v[132:135], v[0:1], off offset:288
	global_load_dwordx4 v[136:139], v[0:1], off offset:320
	global_load_dwordx4 v[140:143], v[0:1], off offset:352
	v_or_b32_e32 v0, s6, v3
	s_mov_b32 s0, 0x2aaaaaab
	v_mul_hi_i32 v1, v0, s0
	v_lshrrev_b32_e32 v7, 31, v1
	v_ashrrev_i32_e32 v1, 6, v1
	v_add_u32_e32 v1, v1, v7
	v_mul_i32_i24_e32 v7, 0x180, v1
	v_sub_u32_e32 v7, v0, v7
	v_ashrrev_i32_e32 v7, 4, v7
	v_lshrrev_b32_e32 v8, 1, v1
	v_bitop3_b32 v7, v8, v7, 7 bitop3:0x6c
	v_mul_i32_i24_e32 v1, 0xc0, v1
	v_lshl_add_u32 v146, v7, 3, v1
	v_add_u32_e32 v1, 0x2000, v0
	v_mul_hi_i32 v7, v1, s0
	v_lshrrev_b32_e32 v8, 31, v7
	v_ashrrev_i32_e32 v7, 6, v7
	v_add_u32_e32 v7, v7, v8
	v_mul_i32_i24_e32 v8, 0x180, v7
	v_sub_u32_e32 v1, v1, v8
	v_ashrrev_i32_e32 v1, 4, v1
	v_lshrrev_b32_e32 v8, 1, v7
	v_bitop3_b32 v1, v8, v1, 7 bitop3:0x6c
	v_mul_i32_i24_e32 v7, 0xc0, v7
	v_add_u32_e32 v0, 0x4000, v0
	v_lshl_add_u32 v148, v1, 3, v7
	v_mul_hi_i32 v1, v0, s0
	v_lshrrev_b32_e32 v7, 31, v1
	v_ashrrev_i32_e32 v1, 6, v1
	v_add_u32_e32 v1, v1, v7
	v_mul_i32_i24_e32 v7, 0x180, v1
	v_sub_u32_e32 v0, v0, v7
	v_ashrrev_i32_e32 v0, 4, v0
	v_lshrrev_b32_e32 v7, 1, v1
	v_bitop3_b32 v0, v7, v0, 7 bitop3:0x6c
	v_mul_i32_i24_e32 v1, 0xc0, v1
	v_lshlrev_b32_e32 v7, 3, v5
	s_lshl_b32 s0, s3, 6
	v_lshl_add_u32 v150, v0, 3, v1
	v_and_b32_e32 v1, 32, v4
	s_and_b32 s0, s0, 64
	v_and_b32_e32 v8, 24, v7
	v_or3_b32 v1, v8, v1, s0
	s_ashr_i32 s0, s6, 8
	s_and_b32 s1, s0, 0xfffff0
	s_lshr_b32 s0, s0, 1
	v_bfe_u32 v0, v4, 2, 2
	s_and_b32 s0, s0, 4
	v_and_or_b32 v0, v2, 8, v0
	s_or_b32 s0, s1, s0
	v_or_b32_e32 v8, s0, v0
	s_add_i32 s0, s6, 0x2000
	s_ashr_i32 s0, s0, 8
	s_lshl_b32 s2, s64, 2
	s_and_b32 s1, s0, 0xfffff0
	s_lshr_b32 s0, s0, 1
	s_and_b32 s2, s2, 28
	s_and_b32 s0, s0, 4
	s_or_b32 s0, s1, s0
	s_mulk_i32 s2, 0x6000
	v_or_b32_e32 v0, s0, v0
	s_add_u32 s0, s4, s2
	s_addc_u32 s1, s5, 0
	s_add_i32 s30, s6, 0
	v_ashrrev_i32_e32 v147, 31, v146
	v_mad_i32_i24 v152, v8, s60, v1
	v_mad_i32_i24 v154, v0, s60, v1
	s_add_i32 m0, s30, 0x8000
	v_lshl_add_u64 v[0:1], v[146:147], 1, s[0:1]
	v_ashrrev_i32_e32 v149, 31, v148
	s_waitcnt lgkmcnt(0)
	global_load_lds_dwordx4 v[0:1], off
	v_lshl_add_u64 v[0:1], v[148:149], 1, s[0:1]
	s_add_i32 m0, s30, 0xa000
	v_ashrrev_i32_e32 v151, 31, v150
	global_load_lds_dwordx4 v[0:1], off
	v_lshl_add_u64 v[0:1], v[150:151], 1, s[0:1]
	s_add_i32 m0, s30, 0xc000
	v_ashrrev_i32_e32 v153, 31, v152
	global_load_lds_dwordx4 v[0:1], off
	v_lshl_add_u64 v[0:1], v[152:153], 1, s[0:1]
	s_mov_b32 m0, s30
	v_ashrrev_i32_e32 v155, 31, v154
	global_load_lds_dwordx4 v[0:1], off
	v_lshl_add_u64 v[0:1], v[154:155], 1, s[0:1]
	s_add_i32 m0, s30, 0x2000
	s_cmp_lg_u32 0, -1
	global_load_lds_dwordx4 v[0:1], off
	s_cselect_b32 s0, 0, 0
	s_add_i32 s1, s0, 0x8000
	v_lshlrev_b32_e32 v8, 1, v4
	v_lshlrev_b32_e32 v1, 3, v4
	v_mov_b32_e32 v4, s1
	s_movk_i32 s1, 0x180
	v_and_b32_e32 v1, 0x70, v1
	v_mad_u32_u24 v161, v6, s1, v4
	s_movk_i32 s1, 0x60
	v_and_b32_e32 v0, 32, v8
	v_bitop3_b32 v165, v184, v1, s1 bitop3:0x36
	s_movk_i32 s1, 0x118
	v_and_b32_e32 v3, 0xc0, v3
	v_and_or_b32 v0, v7, s1, v0
	v_add3_u32 v166, v3, s0, v0
	s_and_b32 s0, s64, 7
	v_mov_b32_e32 v14, v185
	v_mov_b32_e32 v15, v185
	v_bitop3_b32 v162, v2, v1, 16 bitop3:0x6c
	v_bitop3_b32 v163, v184, v1, 32 bitop3:0x36
	v_bitop3_b32 v164, v184, v1, 64 bitop3:0x36
	v_cmp_gt_u32_e64 s[6:7], 32, v5
	v_lshl_add_u32 v160, v6, 2, v159
	s_lshl_b32 s0, s0, 8
	v_mov_b32_e32 v0, v185
	v_mov_b32_e32 v1, v185
	v_mov_b32_e32 v2, v185
	v_mov_b32_e32 v3, v185
	v_mov_b32_e32 v4, v185
	v_mov_b32_e32 v5, v185
	v_mov_b32_e32 v6, v185
	v_mov_b32_e32 v7, v185
	v_mov_b32_e32 v8, v185
	v_mov_b32_e32 v9, v185
	v_mov_b32_e32 v10, v185
	v_mov_b32_e32 v11, v185
	v_mov_b32_e32 v12, v185
	v_mov_b32_e32 v13, v185
	v_mov_b64_e32 v[30:31], v[14:15]
	v_mov_b64_e32 v[46:47], v[14:15]
	v_mov_b64_e32 v[62:63], v[14:15]
	s_mov_b32 s31, 0
	s_or_b32 s34, s0, 64
	v_lshlrev_b32_e32 v212, 1, v146
	v_lshlrev_b32_e32 v213, 1, v148
	v_lshlrev_b32_e32 v214, 1, v150
	v_lshlrev_b32_e32 v215, 1, v152
	v_lshlrev_b32_e32 v216, 1, v154
	v_mov_b32_e32 v167, 0
	v_mov_b32_e32 v196, 0x80000000
	v_mov_b32_e32 v197, 0x80000000
	v_mov_b32_e32 v198, 0x80000000
	v_mov_b32_e32 v199, 0x80000000
	v_mov_b32_e32 v200, 0x80000000
	v_mov_b32_e32 v201, 0x80000000
	v_mov_b32_e32 v202, 0x80000000
	v_mov_b32_e32 v203, 0x80000000
	v_mov_b32_e32 v204, 0x80000000
	v_mov_b32_e32 v205, 0x80000000
	v_mov_b32_e32 v206, 0x80000000
	v_mov_b32_e32 v207, 0x80000000
	v_mov_b32_e32 v208, 0x80000000
	v_mov_b32_e32 v209, 0x80000000
	v_mov_b32_e32 v210, 0x80000000
	v_mov_b32_e32 v211, 0x80000000
	v_mov_b64_e32 v[28:29], v[12:13]
	v_mov_b64_e32 v[26:27], v[10:11]
	v_mov_b64_e32 v[24:25], v[8:9]
	v_mov_b64_e32 v[22:23], v[6:7]
	v_mov_b64_e32 v[20:21], v[4:5]
	v_mov_b64_e32 v[18:19], v[2:3]
	v_mov_b64_e32 v[16:17], v[0:1]
	v_mov_b64_e32 v[44:45], v[12:13]
	v_mov_b64_e32 v[42:43], v[10:11]
	v_mov_b64_e32 v[40:41], v[8:9]
	v_mov_b64_e32 v[38:39], v[6:7]
	v_mov_b64_e32 v[36:37], v[4:5]
	v_mov_b64_e32 v[34:35], v[2:3]
	v_mov_b64_e32 v[32:33], v[0:1]
	v_mov_b64_e32 v[60:61], v[12:13]
	v_mov_b64_e32 v[58:59], v[10:11]
	v_mov_b64_e32 v[56:57], v[8:9]
	v_mov_b64_e32 v[54:55], v[6:7]
	v_mov_b64_e32 v[52:53], v[4:5]
	v_mov_b64_e32 v[50:51], v[2:3]
	v_mov_b64_e32 v[48:49], v[0:1]
	v_mov_b32_e32 v168, 0
	s_waitcnt vmcnt(0) lgkmcnt(0)
	s_barrier
	s_and_b32 s35, s31, 1
	v_add_u32_e32 v156, v161, v162
	ds_read_b128 v[236:239], v156 offset:0
	ds_read_b128 v[240:243], v156 offset:0x3000
	s_cmp_eq_u32 s31, 31
	s_cbranch_scc1 .LBB0_171
